# last-layer R3 (update only): own fast body with LDS-shared gate chunks and mid-iteration prefetch, replacing the older per-wave batched body
# speedup vs baseline: 1.0105x; 1.0105x over previous
.LBB0_149:
	s_cmp_lg_u64 s[4:5], 0
	s_cbranch_scc0 .Lr3n_entry
	s_cmp_lg_u32 s99, 0
	s_cbranch_scc0 .Lr3_slow_cold
	s_add_i32 s8, s44, s19
	s_mul_hi_i32 s9, s8, 0x78787879
	s_lshr_b32 s25, s9, 31
	s_ashr_i32 s9, s9, 11
	s_add_i32 s9, s9, s25
	s_mul_i32 s25, s9, 0xffffef00
	s_add_i32 s25, s8, s25
	s_cmpk_gt_i32 s25, 0xff
	s_cselect_b64 s[52:53], -1, 0
	s_branch .Lr3_slow_pfa

.Lr3_slow_u:
	s_and_b64 s[46:47], s[50:51], s[52:53]
	s_cmp_lg_u64 s[46:47], 0
	s_cbranch_scc0 .Lr3_slow
	v_lshlrev_b32_e32 v160, 2, v36
	s_add_i32 s72, s7, 0xffffff00
	s_cmp_lg_u64 s[50:51], 0
	s_cselect_b32 s27, s22, s49
	s_cselect_b32 s32, s23, s55
	s_cselect_b32 s37, 24, 20
	s_cselect_b32 s72, s72, s7
	s_cselect_b32 s85, s6, 8
	s_mov_b32 s40, s6
	s_mov_b32 s41, 0
	s_lshl_b64 s[40:41], s[40:41], s37
	s_add_u32 s40, s27, s40
	s_addc_u32 s41, s32, s41
	s_lshl_b32 s72, s72, 12
	s_add_u32 s40, s40, s72
	s_addc_u32 s41, s41, 0
	s_add_i32 s27, s85, s3
	s_mul_hi_i32 s32, s27, 0x6000
	s_mulk_i32 s27, 0x6000
	s_add_u32 s66, s34, s27
	s_addc_u32 s67, s35, s32
	s_add_u32 s66, s66, 0x5000
	s_addc_u32 s67, s67, 0
	s_add_i32 s27, s85, s13
	s_mul_hi_i32 s32, s27, 0x6000
	s_mulk_i32 s27, 0x6000
	s_add_u32 s38, s34, s27
	s_addc_u32 s39, s35, s32
	s_add_u32 s46, s38, 0x1000
	s_addc_u32 s47, s39, 0
	global_load_dwordx4 v[12:15], v160, s[40:41] nt
	global_load_dwordx4 v[8:11], v160, s[40:41] offset:1024 nt
	global_load_dwordx4 v[4:7], v160, s[40:41] offset:2048 nt
	global_load_dwordx4 v[0:3], v160, s[40:41] offset:3072 nt
	global_load_dwordx2 v[54:55], v[46:47], off offset:-1536 nt
	global_load_dwordx2 v[52:53], v[46:47], off offset:-1024 nt
	global_load_dwordx2 v[50:51], v[46:47], off offset:-512 nt
	global_load_dwordx2 v[48:49], v[46:47], off nt
	global_load_dwordx4 v[64:67], v160, s[66:67]
	global_load_dwordx4 v[68:71], v160, s[66:67] offset:1024
	global_load_dwordx4 v[72:75], v160, s[66:67] offset:2048
	global_load_dwordx4 v[76:79], v160, s[66:67] offset:3072
	s_mov_b32 s6, s8
	s_ashr_i32 s7, s8, 31
	s_lshl_b64 s[6:7], s[6:7], 11
	v_lshl_add_u64 v[250:251], v[38:39], 0, s[6:7]
	s_mov_b64 s[6:7], s[52:53]
	s_add_i32 s72, s25, 0xffffff00
	s_cmp_lg_u64 s[6:7], 0
	s_cselect_b32 s27, s22, s49
	s_cselect_b32 s32, s23, s55
	s_cselect_b32 s37, 24, 20
	s_cselect_b32 s72, s72, s25
	s_cselect_b32 s85, s9, 8
	s_mov_b32 s64, s9
	s_mov_b32 s65, 0
	s_lshl_b64 s[64:65], s[64:65], s37
	s_add_u32 s64, s27, s64
	s_addc_u32 s65, s32, s65
	s_lshl_b32 s72, s72, 12
	s_add_u32 s64, s64, s72
	s_addc_u32 s65, s65, 0
	s_add_i32 s27, s85, s3
	s_mul_hi_i32 s32, s27, 0x6000
	s_mulk_i32 s27, 0x6000
	s_add_u32 s10, s34, s27
	s_addc_u32 s11, s35, s32
	s_add_u32 s10, s10, 0x5000
	s_addc_u32 s11, s11, 0
	s_add_i32 s27, s85, s13
	s_mul_hi_i32 s32, s27, 0x6000
	s_mulk_i32 s27, 0x6000
	s_add_u32 s50, s34, s27
	s_addc_u32 s51, s35, s32
	s_add_u32 s52, s50, 0x1000
	s_addc_u32 s53, s51, 0
	global_load_dwordx4 v[16:19], v160, s[64:65] nt
	global_load_dwordx4 v[20:23], v160, s[64:65] offset:1024 nt
	global_load_dwordx4 v[24:27], v160, s[64:65] offset:2048 nt
	global_load_dwordx4 v[28:31], v160, s[64:65] offset:3072 nt
	global_load_dwordx2 v[62:63], v[250:251], off nt
	global_load_dwordx2 v[60:61], v[250:251], off offset:512 nt
	global_load_dwordx2 v[58:59], v[250:251], off offset:1024 nt
	global_load_dwordx2 v[56:57], v[250:251], off offset:1536 nt
	global_load_dwordx4 v[188:191], v160, s[10:11]
	global_load_dwordx4 v[192:195], v160, s[10:11] offset:1024
	global_load_dwordx4 v[196:199], v160, s[10:11] offset:2048
	global_load_dwordx4 v[96:99], v160, s[10:11] offset:3072
	s_waitcnt vmcnt(16)
	v_lshlrev_b32_e32 v32, 16, v54
	v_and_b32_e32 v33, 0xffff0000, v54
	v_lshlrev_b32_e32 v34, 16, v55
	v_and_b32_e32 v35, 0xffff0000, v55
	v_pk_mul_f32 v[166:167], v[32:33], v[32:33]
	v_pk_mul_f32 v[168:169], v[34:35], v[34:35]
	v_lshlrev_b32_e32 v32, 16, v52
	v_and_b32_e32 v33, 0xffff0000, v52
	v_lshlrev_b32_e32 v34, 16, v53
	v_and_b32_e32 v35, 0xffff0000, v53
	v_pk_fma_f32 v[166:167], v[32:33], v[32:33], v[166:167]
	v_pk_fma_f32 v[168:169], v[34:35], v[34:35], v[168:169]
	v_lshlrev_b32_e32 v32, 16, v50
	v_and_b32_e32 v33, 0xffff0000, v50
	v_lshlrev_b32_e32 v34, 16, v51
	v_and_b32_e32 v35, 0xffff0000, v51
	v_pk_fma_f32 v[166:167], v[32:33], v[32:33], v[166:167]
	v_pk_fma_f32 v[168:169], v[34:35], v[34:35], v[168:169]
	v_lshlrev_b32_e32 v32, 16, v48
	v_and_b32_e32 v33, 0xffff0000, v48
	v_lshlrev_b32_e32 v34, 16, v49
	v_and_b32_e32 v35, 0xffff0000, v49
	v_pk_fma_f32 v[166:167], v[32:33], v[32:33], v[166:167]
	v_pk_fma_f32 v[168:169], v[34:35], v[34:35], v[168:169]
	v_pk_add_f32 v[166:167], v[166:167], v[168:169]
	s_nop 0
	v_add_f32_e32 v164, v166, v167
	v_mov_b32_e32 v165, v164
	s_nop 1
	v_permlane32_swap_b32_e32 v165, v164
	v_add_f32_e32 v164, v164, v165
	v_mov_b32_e32 v165, v164
	s_nop 1
	v_permlane16_swap_b32_e32 v165, v164
	v_add_f32_e32 v164, v164, v165
	s_nop 1
	v_add_f32_dpp v164, v164, v164 row_ror:8 row_mask:0xf bank_mask:0xf
	s_nop 1
	v_add_f32_dpp v164, v164, v164 row_ror:4 row_mask:0xf bank_mask:0xf
	s_nop 1
	v_add_f32_dpp v164, v164, v164 row_ror:2 row_mask:0xf bank_mask:0xf
	s_nop 1
	v_add_f32_dpp v164, v164, v164 row_ror:1 row_mask:0xf bank_mask:0xf
	s_nop 0
	v_fmamk_f32 v164, v164, 0x3a800000, v200
	v_rsq_f32_e32 v164, v164
	v_lshlrev_b32_e32 v32, 16, v54
	v_and_b32_e32 v33, 0xffff0000, v54
	v_lshlrev_b32_e32 v34, 16, v55
	v_and_b32_e32 v35, 0xffff0000, v55
	v_pk_mul_f32 v[32:33], v[32:33], v[164:165] op_sel_hi:[1,0]
	v_pk_mul_f32 v[34:35], v[34:35], v[164:165] op_sel_hi:[1,0]
	v_pk_mul_f32 v[32:33], v[218:219], v[32:33]
	v_pk_mul_f32 v[34:35], v[220:221], v[34:35]
	s_waitcnt vmcnt(15)
	v_pk_fma_f32 v[12:13], v[64:65], v[32:33], v[12:13]
	v_pk_fma_f32 v[14:15], v[66:67], v[34:35], v[14:15]
	global_store_dwordx4 v160, v[12:15], s[40:41] nt
	v_lshlrev_b32_e32 v32, 16, v52
	v_and_b32_e32 v33, 0xffff0000, v52
	v_lshlrev_b32_e32 v34, 16, v53
	v_and_b32_e32 v35, 0xffff0000, v53
	v_pk_mul_f32 v[32:33], v[32:33], v[164:165] op_sel_hi:[1,0]
	v_pk_mul_f32 v[34:35], v[34:35], v[164:165] op_sel_hi:[1,0]
	v_pk_mul_f32 v[32:33], v[222:223], v[32:33]
	v_pk_mul_f32 v[34:35], v[224:225], v[34:35]
	s_waitcnt vmcnt(15)
	v_pk_fma_f32 v[8:9], v[68:69], v[32:33], v[8:9]
	v_pk_fma_f32 v[10:11], v[70:71], v[34:35], v[10:11]
	global_store_dwordx4 v160, v[8:11], s[40:41] offset:1024 nt
	v_lshlrev_b32_e32 v32, 16, v50
	v_and_b32_e32 v33, 0xffff0000, v50
	v_lshlrev_b32_e32 v34, 16, v51
	v_and_b32_e32 v35, 0xffff0000, v51
	v_pk_mul_f32 v[32:33], v[32:33], v[164:165] op_sel_hi:[1,0]
	v_pk_mul_f32 v[34:35], v[34:35], v[164:165] op_sel_hi:[1,0]
	v_pk_mul_f32 v[32:33], v[226:227], v[32:33]
	v_pk_mul_f32 v[34:35], v[228:229], v[34:35]
	s_waitcnt vmcnt(15)
	v_pk_fma_f32 v[4:5], v[72:73], v[32:33], v[4:5]
	v_pk_fma_f32 v[6:7], v[74:75], v[34:35], v[6:7]
	global_store_dwordx4 v160, v[4:7], s[40:41] offset:2048 nt
	v_lshlrev_b32_e32 v32, 16, v48
	v_and_b32_e32 v33, 0xffff0000, v48
	v_lshlrev_b32_e32 v34, 16, v49
	v_and_b32_e32 v35, 0xffff0000, v49
	v_pk_mul_f32 v[32:33], v[32:33], v[164:165] op_sel_hi:[1,0]
	v_pk_mul_f32 v[34:35], v[34:35], v[164:165] op_sel_hi:[1,0]
	v_pk_mul_f32 v[32:33], v[230:231], v[32:33]
	v_pk_mul_f32 v[34:35], v[232:233], v[34:35]
	s_waitcnt vmcnt(15)
	v_pk_fma_f32 v[0:1], v[76:77], v[32:33], v[0:1]
	v_pk_fma_f32 v[2:3], v[78:79], v[34:35], v[2:3]
	global_store_dwordx4 v160, v[0:3], s[40:41] offset:3072 nt
	s_waitcnt vmcnt(8)
	v_lshlrev_b32_e32 v32, 16, v62
	v_and_b32_e32 v33, 0xffff0000, v62
	v_lshlrev_b32_e32 v34, 16, v63
	v_and_b32_e32 v35, 0xffff0000, v63
	v_pk_mul_f32 v[166:167], v[32:33], v[32:33]
	v_pk_mul_f32 v[168:169], v[34:35], v[34:35]
	v_lshlrev_b32_e32 v32, 16, v60
	v_and_b32_e32 v33, 0xffff0000, v60
	v_lshlrev_b32_e32 v34, 16, v61
	v_and_b32_e32 v35, 0xffff0000, v61
	v_pk_fma_f32 v[166:167], v[32:33], v[32:33], v[166:167]
	v_pk_fma_f32 v[168:169], v[34:35], v[34:35], v[168:169]
	v_lshlrev_b32_e32 v32, 16, v58
	v_and_b32_e32 v33, 0xffff0000, v58
	v_lshlrev_b32_e32 v34, 16, v59
	v_and_b32_e32 v35, 0xffff0000, v59
	v_pk_fma_f32 v[166:167], v[32:33], v[32:33], v[166:167]
	v_pk_fma_f32 v[168:169], v[34:35], v[34:35], v[168:169]
	v_lshlrev_b32_e32 v32, 16, v56
	v_and_b32_e32 v33, 0xffff0000, v56
	v_lshlrev_b32_e32 v34, 16, v57
	v_and_b32_e32 v35, 0xffff0000, v57
	v_pk_fma_f32 v[166:167], v[32:33], v[32:33], v[166:167]
	v_pk_fma_f32 v[168:169], v[34:35], v[34:35], v[168:169]
	v_pk_add_f32 v[166:167], v[166:167], v[168:169]
	s_nop 0
	v_add_f32_e32 v164, v166, v167
	v_mov_b32_e32 v165, v164
	s_nop 1
	v_permlane32_swap_b32_e32 v165, v164
	v_add_f32_e32 v164, v164, v165
	v_mov_b32_e32 v165, v164
	s_nop 1
	v_permlane16_swap_b32_e32 v165, v164
	v_add_f32_e32 v164, v164, v165
	s_nop 1
	v_add_f32_dpp v164, v164, v164 row_ror:8 row_mask:0xf bank_mask:0xf
	s_nop 1
	v_add_f32_dpp v164, v164, v164 row_ror:4 row_mask:0xf bank_mask:0xf
	s_nop 1
	v_add_f32_dpp v164, v164, v164 row_ror:2 row_mask:0xf bank_mask:0xf
	s_nop 1
	v_add_f32_dpp v164, v164, v164 row_ror:1 row_mask:0xf bank_mask:0xf
	s_nop 0
	v_fmamk_f32 v164, v164, 0x3a800000, v200
	v_rsq_f32_e32 v164, v164
	v_lshlrev_b32_e32 v32, 16, v62
	v_and_b32_e32 v33, 0xffff0000, v62
	v_lshlrev_b32_e32 v34, 16, v63
	v_and_b32_e32 v35, 0xffff0000, v63
	v_pk_mul_f32 v[32:33], v[32:33], v[164:165] op_sel_hi:[1,0]
	v_pk_mul_f32 v[34:35], v[34:35], v[164:165] op_sel_hi:[1,0]
	v_pk_mul_f32 v[32:33], v[218:219], v[32:33]
	v_pk_mul_f32 v[34:35], v[220:221], v[34:35]
	s_waitcnt vmcnt(7)
	v_pk_fma_f32 v[16:17], v[188:189], v[32:33], v[16:17]
	v_pk_fma_f32 v[18:19], v[190:191], v[34:35], v[18:19]
	global_store_dwordx4 v160, v[16:19], s[64:65] nt
	v_lshlrev_b32_e32 v32, 16, v60
	v_and_b32_e32 v33, 0xffff0000, v60
	v_lshlrev_b32_e32 v34, 16, v61
	v_and_b32_e32 v35, 0xffff0000, v61
	v_pk_mul_f32 v[32:33], v[32:33], v[164:165] op_sel_hi:[1,0]
	v_pk_mul_f32 v[34:35], v[34:35], v[164:165] op_sel_hi:[1,0]
	v_pk_mul_f32 v[32:33], v[222:223], v[32:33]
	v_pk_mul_f32 v[34:35], v[224:225], v[34:35]
	s_waitcnt vmcnt(7)
	v_pk_fma_f32 v[20:21], v[192:193], v[32:33], v[20:21]
	v_pk_fma_f32 v[22:23], v[194:195], v[34:35], v[22:23]
	global_store_dwordx4 v160, v[20:23], s[64:65] offset:1024 nt
	v_lshlrev_b32_e32 v32, 16, v58
	v_and_b32_e32 v33, 0xffff0000, v58
	v_lshlrev_b32_e32 v34, 16, v59
	v_and_b32_e32 v35, 0xffff0000, v59
	v_pk_mul_f32 v[32:33], v[32:33], v[164:165] op_sel_hi:[1,0]
	v_pk_mul_f32 v[34:35], v[34:35], v[164:165] op_sel_hi:[1,0]
	v_pk_mul_f32 v[32:33], v[226:227], v[32:33]
	v_pk_mul_f32 v[34:35], v[228:229], v[34:35]
	s_waitcnt vmcnt(7)
	v_pk_fma_f32 v[24:25], v[196:197], v[32:33], v[24:25]
	v_pk_fma_f32 v[26:27], v[198:199], v[34:35], v[26:27]
	global_store_dwordx4 v160, v[24:27], s[64:65] offset:2048 nt
	v_lshlrev_b32_e32 v32, 16, v56
	v_and_b32_e32 v33, 0xffff0000, v56
	v_lshlrev_b32_e32 v34, 16, v57
	v_and_b32_e32 v35, 0xffff0000, v57
	v_pk_mul_f32 v[32:33], v[32:33], v[164:165] op_sel_hi:[1,0]
	v_pk_mul_f32 v[34:35], v[34:35], v[164:165] op_sel_hi:[1,0]
	v_pk_mul_f32 v[32:33], v[230:231], v[32:33]
	v_pk_mul_f32 v[34:35], v[232:233], v[34:35]
	s_waitcnt vmcnt(7)
	v_pk_fma_f32 v[28:29], v[96:97], v[32:33], v[28:29]
	v_pk_fma_f32 v[30:31], v[98:99], v[34:35], v[30:31]
	global_store_dwordx4 v160, v[28:31], s[64:65] offset:3072 nt
	s_branch .LBB0_148
.Lr3n_entry:
	s_cmp_lg_u32 s99, 0
	s_cbranch_scc0 .Lr3n_cold
	s_add_i32 s8, s44, s19
	s_mul_hi_i32 s9, s8, 0x78787879
	s_lshr_b32 s25, s9, 31
	s_ashr_i32 s9, s9, 11
	s_add_i32 s9, s9, s25
	s_mul_i32 s25, s9, 0xffffef00
	s_add_i32 s25, s8, s25
	s_cmpk_gt_i32 s25, 0xff
	s_cselect_b64 s[52:53], -1, 0
	s_branch .Lr3n_pfa
.Lr3n_cold:
	s_mul_hi_i32 s6, s19, 0x78787879
	s_lshr_b32 s7, s6, 31
	s_ashr_i32 s6, s6, 11
	s_add_i32 s6, s6, s7
	s_mul_i32 s7, s6, 0xffffef00
	s_add_i32 s7, s19, s7
	s_cmpk_gt_i32 s7, 0xff
	s_cselect_b64 s[50:51], -1, 0
	s_add_i32 s8, s44, s19
	s_cmp_lt_i32 s8, 0x8800
	s_cbranch_scc0 .Lr3_slow
	s_mul_hi_i32 s9, s8, 0x78787879
	s_lshr_b32 s25, s9, 31
	s_ashr_i32 s9, s9, 11
	s_add_i32 s9, s9, s25
	s_mul_i32 s25, s9, 0xffffef00
	s_add_i32 s25, s8, s25
	s_cmpk_gt_i32 s25, 0xff
	s_cselect_b64 s[52:53], -1, 0
	s_and_b64 s[46:47], s[50:51], s[52:53]
	s_or_b64 s[46:47], s[46:47], s[4:5]
	s_cmp_lg_u64 s[46:47], 0
	s_cbranch_scc0 .Lr3_slow
	v_lshlrev_b32_e32 v160, 2, v36
	s_add_i32 s72, s7, 0xffffff00
	s_cmp_lg_u64 s[50:51], 0
	s_cselect_b32 s27, s22, s49
	s_cselect_b32 s32, s23, s55
	s_cselect_b32 s37, 24, 20
	s_cselect_b32 s72, s72, s7
	s_mov_b32 s40, s6
	s_mov_b32 s41, 0
	s_lshl_b64 s[40:41], s[40:41], s37
	s_add_u32 s40, s27, s40
	s_addc_u32 s41, s32, s41
	s_lshl_b32 s72, s72, 12
	s_add_u32 s40, s40, s72
	s_addc_u32 s41, s41, 0
	s_cmp_lg_u32 s99, 0
	s_cbranch_scc1 .Lr3n_pfa
	global_load_dwordx4 v[12:15], v160, s[40:41] nt
	global_load_dwordx4 v[8:11], v160, s[40:41] offset:1024 nt
	global_load_dwordx4 v[4:7], v160, s[40:41] offset:2048 nt
	global_load_dwordx4 v[0:3], v160, s[40:41] offset:3072 nt
	global_load_dwordx2 v[54:55], v[46:47], off offset:-1536 nt
	global_load_dwordx2 v[52:53], v[46:47], off offset:-1024 nt
	global_load_dwordx2 v[50:51], v[46:47], off offset:-512 nt
	global_load_dwordx2 v[48:49], v[46:47], off nt

.Lr3n_pf:
	global_load_dwordx4 v[16:19], v160, s[64:65] nt
	global_load_dwordx4 v[20:23], v160, s[64:65] offset:1024 nt
	global_load_dwordx4 v[24:27], v160, s[64:65] offset:2048 nt
	global_load_dwordx4 v[28:31], v160, s[64:65] offset:3072 nt
	global_load_dwordx2 v[62:63], v[250:251], off nt
	global_load_dwordx2 v[60:61], v[250:251], off offset:512 nt
	global_load_dwordx2 v[58:59], v[250:251], off offset:1024 nt
	global_load_dwordx2 v[56:57], v[250:251], off offset:1536 nt
	s_waitcnt vmcnt(12)
.Lr3n_proc:
	s_barrier
	v_add_u32_e32 v37, s93, v160
	ds_read_b128 v[64:67], v37
	ds_read_b128 v[68:71], v37 offset:1024
	ds_read_b128 v[72:75], v37 offset:2048
	ds_read_b128 v[76:79], v37 offset:3072
	v_lshlrev_b32_e32 v172, 16, v54
	v_and_b32_e32 v173, 0xffff0000, v54
	v_lshlrev_b32_e32 v174, 16, v55
	v_and_b32_e32 v175, 0xffff0000, v55
	v_pk_mul_f32 v[166:167], v[172:173], v[172:173]
	v_pk_mul_f32 v[168:169], v[174:175], v[174:175]
	v_lshlrev_b32_e32 v176, 16, v52
	v_and_b32_e32 v177, 0xffff0000, v52
	v_lshlrev_b32_e32 v178, 16, v53
	v_and_b32_e32 v179, 0xffff0000, v53
	v_pk_fma_f32 v[166:167], v[176:177], v[176:177], v[166:167]
	v_pk_fma_f32 v[168:169], v[178:179], v[178:179], v[168:169]
	v_lshlrev_b32_e32 v180, 16, v50
	v_and_b32_e32 v181, 0xffff0000, v50
	v_lshlrev_b32_e32 v182, 16, v51
	v_and_b32_e32 v183, 0xffff0000, v51
	v_pk_fma_f32 v[166:167], v[180:181], v[180:181], v[166:167]
	v_pk_fma_f32 v[168:169], v[182:183], v[182:183], v[168:169]
	v_lshlrev_b32_e32 v184, 16, v48
	v_and_b32_e32 v185, 0xffff0000, v48
	v_lshlrev_b32_e32 v186, 16, v49
	v_and_b32_e32 v187, 0xffff0000, v49
	v_pk_fma_f32 v[166:167], v[184:185], v[184:185], v[166:167]
	v_pk_fma_f32 v[168:169], v[186:187], v[186:187], v[168:169]
	v_pk_add_f32 v[166:167], v[166:167], v[168:169]
	s_nop 0
	v_add_f32_e32 v164, v166, v167
	v_mov_b32_e32 v165, v164
	s_nop 1
	v_permlane32_swap_b32_e32 v165, v164
	v_add_f32_e32 v164, v164, v165
	v_mov_b32_e32 v165, v164
	s_nop 1
	v_permlane16_swap_b32_e32 v165, v164
	v_add_f32_e32 v164, v164, v165
	s_nop 1
	v_add_f32_dpp v164, v164, v164 row_ror:8 row_mask:0xf bank_mask:0xf
	s_nop 1
	v_add_f32_dpp v164, v164, v164 row_ror:4 row_mask:0xf bank_mask:0xf
	s_nop 1
	v_add_f32_dpp v164, v164, v164 row_ror:2 row_mask:0xf bank_mask:0xf
	s_nop 1
	v_add_f32_dpp v164, v164, v164 row_ror:1 row_mask:0xf bank_mask:0xf
	s_nop 0
	v_fmamk_f32 v164, v164, 0x3a800000, v200
	v_rsq_f32_e32 v164, v164
	s_nop 0
	v_pk_mul_f32 v[172:173], v[172:173], v[164:165] op_sel_hi:[1,0]
	v_pk_mul_f32 v[174:175], v[174:175], v[164:165] op_sel_hi:[1,0]
	v_pk_mul_f32 v[172:173], v[218:219], v[172:173]
	v_pk_mul_f32 v[174:175], v[220:221], v[174:175]
	s_waitcnt lgkmcnt(3)
	v_pk_fma_f32 v[12:13], v[64:65], v[172:173], v[12:13]
	v_pk_fma_f32 v[14:15], v[66:67], v[174:175], v[14:15]
	global_store_dwordx4 v160, v[12:15], s[40:41] nt
	v_pk_mul_f32 v[176:177], v[176:177], v[164:165] op_sel_hi:[1,0]
	v_pk_mul_f32 v[178:179], v[178:179], v[164:165] op_sel_hi:[1,0]
	v_pk_mul_f32 v[176:177], v[222:223], v[176:177]
	v_pk_mul_f32 v[178:179], v[224:225], v[178:179]
	s_waitcnt lgkmcnt(2)
	v_pk_fma_f32 v[8:9], v[68:69], v[176:177], v[8:9]
	v_pk_fma_f32 v[10:11], v[70:71], v[178:179], v[10:11]
	global_store_dwordx4 v160, v[8:11], s[40:41] offset:1024 nt
	v_pk_mul_f32 v[180:181], v[180:181], v[164:165] op_sel_hi:[1,0]
	v_pk_mul_f32 v[182:183], v[182:183], v[164:165] op_sel_hi:[1,0]
	v_pk_mul_f32 v[180:181], v[226:227], v[180:181]
	v_pk_mul_f32 v[182:183], v[228:229], v[182:183]
	s_waitcnt lgkmcnt(1)
	v_pk_fma_f32 v[4:5], v[72:73], v[180:181], v[4:5]
	v_pk_fma_f32 v[6:7], v[74:75], v[182:183], v[6:7]
	global_store_dwordx4 v160, v[4:7], s[40:41] offset:2048 nt
	v_pk_mul_f32 v[184:185], v[184:185], v[164:165] op_sel_hi:[1,0]
	v_pk_mul_f32 v[186:187], v[186:187], v[164:165] op_sel_hi:[1,0]
	v_pk_mul_f32 v[184:185], v[230:231], v[184:185]
	v_pk_mul_f32 v[186:187], v[232:233], v[186:187]
	s_waitcnt lgkmcnt(0)
	v_pk_fma_f32 v[0:1], v[76:77], v[184:185], v[0:1]
	v_pk_fma_f32 v[2:3], v[78:79], v[186:187], v[2:3]
	global_store_dwordx4 v160, v[0:3], s[40:41] offset:3072 nt
	ds_read_b128 v[188:191], v37 offset:12288
	ds_read_b128 v[192:195], v37 offset:13312
	ds_read_b128 v[196:199], v37 offset:14336
	ds_read_b128 v[96:99], v37 offset:15360
	s_waitcnt vmcnt(4)
	s_mov_b32 s99, 0
	s_add_i32 s72, s19, s48
	s_cmp_gt_i32 s72, 0x87ff
	s_cbranch_scc1 .Lr3n_nopf
	s_add_i32 s8, s44, s72
	s_cmp_lt_i32 s8, 0x8800
	s_cbranch_scc0 .Lr3n_nopf
	s_mov_b32 s41, s72
	s_mul_hi_i32 s6, s41, 0x78787879
	s_lshr_b32 s7, s6, 31
	s_ashr_i32 s6, s6, 11
	s_add_i32 s6, s6, s7
	s_mul_i32 s7, s6, 0xffffef00
	s_add_i32 s7, s41, s7
	s_cmpk_gt_i32 s7, 0xff
	s_cselect_b64 s[50:51], -1, 0
	s_mul_hi_i32 s9, s8, 0x78787879
	s_lshr_b32 s25, s9, 31
	s_ashr_i32 s9, s9, 11
	s_add_i32 s9, s9, s25
	s_mul_i32 s25, s9, 0xffffef00
	s_add_i32 s25, s8, s25
	s_cmpk_gt_i32 s25, 0xff
	s_cselect_b64 s[52:53], -1, 0
	s_and_b64 s[46:47], s[50:51], s[52:53]
	s_or_b64 s[46:47], s[46:47], s[4:5]
	s_cmp_lg_u64 s[46:47], 0
	s_cbranch_scc0 .Lr3n_nopf
	s_add_i32 s72, s7, 0xffffff00
	s_cmp_lg_u64 s[50:51], 0
	s_cselect_b32 s27, s22, s49
	s_cselect_b32 s32, s23, s55
	s_cselect_b32 s37, 24, 20
	s_cselect_b32 s72, s72, s7
	s_cselect_b32 s85, s6, 8
	s_mov_b32 s40, s6
	s_mov_b32 s41, 0
	s_lshl_b64 s[40:41], s[40:41], s37
	s_add_u32 s40, s27, s40
	s_addc_u32 s41, s32, s41
	s_lshl_b32 s72, s72, 12
	s_add_u32 s40, s40, s72
	s_addc_u32 s41, s41, 0
	s_add_i32 s27, s85, s3
	s_mul_hi_i32 s32, s27, 0x6000
	s_mulk_i32 s27, 0x6000
	s_add_u32 s66, s34, s27
	s_addc_u32 s67, s35, s32
	s_add_u32 s66, s66, 0x5000
	s_addc_u32 s67, s67, 0
	s_add_i32 s27, s85, s13
	s_mul_hi_i32 s32, s27, 0x6000
	s_mulk_i32 s27, 0x6000
	s_add_u32 s38, s34, s27
	s_addc_u32 s39, s35, s32
	s_add_u32 s46, s38, 0x1000
	s_addc_u32 s47, s39, 0
	s_mov_b64 s[6:7], s[52:53]
	s_cmp_lg_u64 s[6:7], 0
	s_cselect_b32 s85, s9, 8
	s_add_i32 s27, s85, s3
	s_mul_hi_i32 s32, s27, 0x6000
	s_mulk_i32 s27, 0x6000
	s_add_u32 s10, s34, s27
	s_addc_u32 s11, s35, s32
	s_add_u32 s10, s10, 0x5000
	s_addc_u32 s11, s11, 0
	s_add_i32 s27, s85, s13
	s_mul_hi_i32 s32, s27, 0x6000
	s_mulk_i32 s27, 0x6000
	s_add_u32 s50, s34, s27
	s_addc_u32 s51, s35, s32
	s_add_u32 s52, s50, 0x1000
	s_addc_u32 s53, s51, 0
	s_xor_b32 s25, s93, 0x6000
	v_lshl_add_u64 v[250:251], v[46:47], 0, s[74:75]
	global_load_dwordx4 v[12:15], v160, s[40:41] nt
	global_load_dwordx4 v[8:11], v160, s[40:41] offset:1024 nt
	global_load_dwordx4 v[4:7], v160, s[40:41] offset:2048 nt
	global_load_dwordx4 v[0:3], v160, s[40:41] offset:3072 nt
	global_load_dwordx2 v[54:55], v[250:251], off offset:-1536 nt
	global_load_dwordx2 v[52:53], v[250:251], off offset:-1024 nt
	global_load_dwordx2 v[50:51], v[250:251], off offset:-512 nt
	global_load_dwordx2 v[48:49], v[250:251], off nt
	s_and_b32 s72, s19, 7
	s_and_b32 s85, s72, 3
	s_lshl_b32 s85, s85, 10
	s_lshl_b32 s37, s72, 10
	s_add_i32 s37, s37, s25
	s_cmp_lt_u32 s72, 4
	s_cselect_b32 s6, s66, s38
	s_cselect_b32 s7, s67, s39
	s_cselect_b32 s8, s46, s10
	s_cselect_b32 s9, s47, s11
	s_cselect_b32 s26, s50, s52
	s_cselect_b32 s27, s51, s53
	s_add_u32 s6, s6, s85
	s_addc_u32 s7, s7, 0
	s_add_u32 s8, s8, s85
	s_addc_u32 s9, s9, 0
	s_add_u32 s26, s26, s85
	s_addc_u32 s27, s27, 0
	s_mov_b32 m0, s37
	s_nop 0
	global_load_lds_dwordx4 v160, s[6:7]
	s_add_i32 s37, s37, 0x2000
	s_mov_b32 m0, s37
	s_nop 0
	global_load_lds_dwordx4 v160, s[8:9]
	s_add_i32 s37, s37, 0x2000
	s_mov_b32 m0, s37
	s_nop 0
	global_load_lds_dwordx4 v160, s[26:27]
	s_mov_b32 s99, 1
.Lr3n_nopf:
	v_lshlrev_b32_e32 v172, 16, v62
	v_and_b32_e32 v173, 0xffff0000, v62
	v_lshlrev_b32_e32 v174, 16, v63
	v_and_b32_e32 v175, 0xffff0000, v63
	v_pk_mul_f32 v[166:167], v[172:173], v[172:173]
	v_pk_mul_f32 v[168:169], v[174:175], v[174:175]
	v_lshlrev_b32_e32 v176, 16, v60
	v_and_b32_e32 v177, 0xffff0000, v60
	v_lshlrev_b32_e32 v178, 16, v61
	v_and_b32_e32 v179, 0xffff0000, v61
	v_pk_fma_f32 v[166:167], v[176:177], v[176:177], v[166:167]
	v_pk_fma_f32 v[168:169], v[178:179], v[178:179], v[168:169]
	v_lshlrev_b32_e32 v180, 16, v58
	v_and_b32_e32 v181, 0xffff0000, v58
	v_lshlrev_b32_e32 v182, 16, v59
	v_and_b32_e32 v183, 0xffff0000, v59
	v_pk_fma_f32 v[166:167], v[180:181], v[180:181], v[166:167]
	v_pk_fma_f32 v[168:169], v[182:183], v[182:183], v[168:169]
	v_lshlrev_b32_e32 v184, 16, v56
	v_and_b32_e32 v185, 0xffff0000, v56
	v_lshlrev_b32_e32 v186, 16, v57
	v_and_b32_e32 v187, 0xffff0000, v57
	v_pk_fma_f32 v[166:167], v[184:185], v[184:185], v[166:167]
	v_pk_fma_f32 v[168:169], v[186:187], v[186:187], v[168:169]
	v_pk_add_f32 v[166:167], v[166:167], v[168:169]
	s_nop 0
	v_add_f32_e32 v164, v166, v167
	v_mov_b32_e32 v165, v164
	s_nop 1
	v_permlane32_swap_b32_e32 v165, v164
	v_add_f32_e32 v164, v164, v165
	v_mov_b32_e32 v165, v164
	s_nop 1
	v_permlane16_swap_b32_e32 v165, v164
	v_add_f32_e32 v164, v164, v165
	s_nop 1
	v_add_f32_dpp v164, v164, v164 row_ror:8 row_mask:0xf bank_mask:0xf
	s_nop 1
	v_add_f32_dpp v164, v164, v164 row_ror:4 row_mask:0xf bank_mask:0xf
	s_nop 1
	v_add_f32_dpp v164, v164, v164 row_ror:2 row_mask:0xf bank_mask:0xf
	s_nop 1
	v_add_f32_dpp v164, v164, v164 row_ror:1 row_mask:0xf bank_mask:0xf
	s_nop 0
	v_fmamk_f32 v164, v164, 0x3a800000, v200
	v_rsq_f32_e32 v164, v164
	s_nop 0
	v_pk_mul_f32 v[172:173], v[172:173], v[164:165] op_sel_hi:[1,0]
	v_pk_mul_f32 v[174:175], v[174:175], v[164:165] op_sel_hi:[1,0]
	v_pk_mul_f32 v[172:173], v[218:219], v[172:173]
	v_pk_mul_f32 v[174:175], v[220:221], v[174:175]
	s_waitcnt lgkmcnt(3)
	v_pk_fma_f32 v[16:17], v[188:189], v[172:173], v[16:17]
	v_pk_fma_f32 v[18:19], v[190:191], v[174:175], v[18:19]
	global_store_dwordx4 v160, v[16:19], s[64:65] nt
	v_pk_mul_f32 v[176:177], v[176:177], v[164:165] op_sel_hi:[1,0]
	v_pk_mul_f32 v[178:179], v[178:179], v[164:165] op_sel_hi:[1,0]
	v_pk_mul_f32 v[176:177], v[222:223], v[176:177]
	v_pk_mul_f32 v[178:179], v[224:225], v[178:179]
	s_waitcnt lgkmcnt(2)
	v_pk_fma_f32 v[20:21], v[192:193], v[176:177], v[20:21]
	v_pk_fma_f32 v[22:23], v[194:195], v[178:179], v[22:23]
	global_store_dwordx4 v160, v[20:23], s[64:65] offset:1024 nt
	v_pk_mul_f32 v[180:181], v[180:181], v[164:165] op_sel_hi:[1,0]
	v_pk_mul_f32 v[182:183], v[182:183], v[164:165] op_sel_hi:[1,0]
	v_pk_mul_f32 v[180:181], v[226:227], v[180:181]
	v_pk_mul_f32 v[182:183], v[228:229], v[182:183]
	s_waitcnt lgkmcnt(1)
	v_pk_fma_f32 v[24:25], v[196:197], v[180:181], v[24:25]
	v_pk_fma_f32 v[26:27], v[198:199], v[182:183], v[26:27]
	global_store_dwordx4 v160, v[24:27], s[64:65] offset:2048 nt
	v_pk_mul_f32 v[184:185], v[184:185], v[164:165] op_sel_hi:[1,0]
	v_pk_mul_f32 v[186:187], v[186:187], v[164:165] op_sel_hi:[1,0]
	v_pk_mul_f32 v[184:185], v[230:231], v[184:185]
	v_pk_mul_f32 v[186:187], v[232:233], v[186:187]
	s_waitcnt lgkmcnt(0)
	v_pk_fma_f32 v[28:29], v[96:97], v[184:185], v[28:29]
	v_pk_fma_f32 v[30:31], v[98:99], v[186:187], v[30:31]
	global_store_dwordx4 v160, v[28:31], s[64:65] offset:3072 nt
	s_xor_b32 s93, s93, 0x6000
	s_branch .LBB0_148
